# stack + p9 K-loop: A-operand LDS-DMA pair issued first in the two 6-DMA load segments (more latency tolerance for the HBM-streamed operand)
# speedup vs baseline: 1.0026x; 1.0026x over previous
; #define PG8_STAGE(bufoff, gbase, voff) do { _Pragma("unroll") for (int _i = 0; _i < 2; ++_i) \
;         __builtin_amdgcn_global_load_lds((const unsigned*)((const char*)(gbase) + (voff)[_i]), (LAS unsigned*)(lds + (bufoff) + ldsw + _i * 8192), 16, 0, 0); } while (0)
; #define PG8_LDA(dst, b, h) do { _Pragma("unroll") for (int m = 0; m < 4; ++m) _Pragma("unroll") for (int k = 0; k < 2; ++k) dst[m][k] = *(const LAS bf16x8*)(lds + PG8_SA(b, h) + aoff + m * 2048 + k * 1024); } while (0)
; #define PG8_LDB(dst, b, h) do { _Pragma("unroll") for (int n = 0; n < 2; ++n) _Pragma("unroll") for (int k = 0; k < 2; ++k) dst[n][k] = *(const LAS bf16x8*)(lds + PG8_SB(b, h) + boff + n * 2048 + k * 1024); } while (0)
; #define PG8_MMA(ai, bj, At, Bt) do { __builtin_amdgcn_s_setprio(1); _Pragma("unroll") for (int m = 0; m < 4; ++m) _Pragma("unroll") for (int n = 0; n < 2; ++n) _Pragma("unroll") for (int k = 0; k < 2; ++k) \
;         acc[ai][bj][m][n] = __builtin_amdgcn_mfma_f32_16x16x32_bf16(Bt[n][k], At[m][k], acc[ai][bj][m][n], 0, 0, 0); __builtin_amdgcn_s_setprio(0); } while (0)
; #define PG8_WAIT_V(n) asm volatile("s_waitcnt vmcnt(" #n ")" ::: "memory")
; #define PG8_WAIT_L(n) asm volatile("s_waitcnt lgkmcnt(" #n ")" ::: "memory")
; #define PG8_BAR __builtin_amdgcn_s_barrier()
; #define PG8_SCHED __builtin_amdgcn_sched_barrier(0)
; template <class Epi>
; __device__ __forceinline__ void gemm_phase(LAS unsigned char* lds, const Gemm g, const StaticOrder& S, const Epi& E, const int tid) {
;     ...
;             PG8_LDB(B0, 0, 0); PG8_LDB(B1, 0, 1); PG8_SCHED; PG8_LDA(At, 0, 0); PG8_STAGE(PG8_SA(1, 1), a1 + hstep, voffA);
;             PG8_WAIT_V(8); PG8_WAIT_L(0); PG8_BAR; PG8_MMA(0, 0, At, B0); PG8_MMA(0, 1, At, B1); PG8_BAR; PG8_SCHED;
;             PG8_LDA(At, 0, 1); PG8_STAGE(PG8_SB(0, 0), b2, voffB); PG8_STAGE(PG8_SB(0, 1), b2 + bhs, voffB); PG8_STAGE(PG8_SA(0, 0), a2, voffA);
;             PG8_WAIT_V(8); PG8_WAIT_L(0); PG8_BAR; PG8_MMA(1, 0, At, B0); PG8_MMA(1, 1, At, B1); PG8_BAR; PG8_SCHED;
.LBB0_126:
	s_add_u32 s30, s28, 0xffe00080
	s_addc_u32 s31, s29, -1
	s_add_i32 s52, 0, 0x10000
	s_cmpk_eq_i32 s51, 0x7c
	s_cselect_b32 s35, s17, s31
	s_cselect_b32 s34, s27, s30
	s_cselect_b32 s31, s15, s50
	s_cselect_b32 s30, s33, s49
	s_add_i32 s54, 0, 0x14000
	v_add_u32_e32 v30, s52, v193
	v_add_u32_e32 v54, s54, v193
	ds_read_b128 v[18:21], v30
	ds_read_b128 v[22:25], v30 offset:1024
	ds_read_b128 v[26:29], v30 offset:2048
	ds_read_b128 v[30:33], v30 offset:3072
	ds_read_b128 v[42:45], v54
	ds_read_b128 v[46:49], v54 offset:1024
	ds_read_b128 v[50:53], v54 offset:2048
	ds_read_b128 v[54:57], v54 offset:3072
	v_lshl_add_u64 v[172:173], s[28:29], 0, v[180:181]
	s_add_i32 m0, s37, 0xc000
	ds_read_b128 v[182:185], v199
	global_load_lds_dwordx4 v[172:173], off
	ds_read_b128 v[186:189], v199 offset:1024
	ds_read_b128 v[212:215], v199 offset:2048
	s_add_i32 m0, s37, 0xe000
	v_lshl_add_u64 v[172:173], s[28:29], 0, v[178:179]
	global_load_lds_dwordx4 v[172:173], off
	ds_read_b128 v[216:219], v199 offset:3072
	ds_read_b128 v[220:223], v199 offset:4096
	ds_read_b128 v[224:227], v199 offset:5120
	ds_read_b128 v[228:231], v199 offset:6144
	ds_read_b128 v[232:235], v199 offset:7168
	s_waitcnt vmcnt(8)
	s_waitcnt lgkmcnt(0)
	s_barrier
	s_setprio 1
	v_mfma_f32_16x16x32_bf16 v[158:161], v[18:21], v[182:185], v[158:161]
	v_mfma_f32_16x16x32_bf16 v[154:157], v[26:29], v[182:185], v[154:157]
	v_mfma_f32_16x16x32_bf16 v[142:145], v[18:21], v[212:215], v[142:145]
	v_mfma_f32_16x16x32_bf16 v[138:141], v[26:29], v[212:215], v[138:141]
	v_mfma_f32_16x16x32_bf16 v[126:129], v[18:21], v[220:223], v[126:129]
	v_mfma_f32_16x16x32_bf16 v[122:125], v[26:29], v[220:223], v[122:125]
	v_mfma_f32_16x16x32_bf16 v[110:113], v[18:21], v[228:231], v[110:113]
	v_mfma_f32_16x16x32_bf16 v[106:109], v[26:29], v[228:231], v[106:109]
	v_mfma_f32_16x16x32_bf16 v[158:161], v[22:25], v[186:189], v[158:161]
	v_mfma_f32_16x16x32_bf16 v[154:157], v[30:33], v[186:189], v[154:157]
	v_mfma_f32_16x16x32_bf16 v[142:145], v[22:25], v[216:219], v[142:145]
	v_mfma_f32_16x16x32_bf16 v[138:141], v[30:33], v[216:219], v[138:141]
	v_mfma_f32_16x16x32_bf16 v[126:129], v[22:25], v[224:227], v[126:129]
	v_mfma_f32_16x16x32_bf16 v[122:125], v[30:33], v[224:227], v[122:125]
	v_mfma_f32_16x16x32_bf16 v[110:113], v[22:25], v[232:235], v[110:113]
	v_mfma_f32_16x16x32_bf16 v[106:109], v[30:33], v[232:235], v[106:109]
	v_mfma_f32_16x16x32_bf16 v[150:153], v[42:45], v[182:185], v[150:153]
	v_mfma_f32_16x16x32_bf16 v[146:149], v[50:53], v[182:185], v[146:149]
	v_mfma_f32_16x16x32_bf16 v[134:137], v[42:45], v[212:215], v[134:137]
	v_mfma_f32_16x16x32_bf16 v[130:133], v[50:53], v[212:215], v[130:133]
	v_mfma_f32_16x16x32_bf16 v[118:121], v[42:45], v[220:223], v[118:121]
	v_mfma_f32_16x16x32_bf16 v[114:117], v[50:53], v[220:223], v[114:117]
	v_mfma_f32_16x16x32_bf16 v[102:105], v[42:45], v[228:231], v[102:105]
	v_mfma_f32_16x16x32_bf16 v[98:101], v[50:53], v[228:231], v[98:101]
	v_mfma_f32_16x16x32_bf16 v[150:153], v[46:49], v[186:189], v[150:153]
	v_mfma_f32_16x16x32_bf16 v[146:149], v[54:57], v[186:189], v[146:149]
	v_mfma_f32_16x16x32_bf16 v[134:137], v[46:49], v[216:219], v[134:137]
	v_mfma_f32_16x16x32_bf16 v[130:133], v[54:57], v[216:219], v[130:133]
	v_mfma_f32_16x16x32_bf16 v[118:121], v[46:49], v[224:227], v[118:121]
	v_mfma_f32_16x16x32_bf16 v[114:117], v[54:57], v[224:227], v[114:117]
	v_mfma_f32_16x16x32_bf16 v[102:105], v[46:49], v[232:235], v[102:105]
	v_mfma_f32_16x16x32_bf16 v[98:101], v[54:57], v[232:235], v[98:101]
	s_setprio 0
	s_barrier
	s_add_i32 s52, s52, s36
	s_mov_b32 m0, s37
	v_lshl_add_u64 v[176:177], s[34:35], 0, v[162:163]
	ds_read_b128 v[182:185], v199 offset:16384
	global_load_lds_dwordx4 v[176:177], off
	s_mov_b32 m0, s38
	v_lshl_add_u64 v[200:201], s[34:35], 0, v[164:165]
	global_load_lds_dwordx4 v[200:201], off
	ds_read_b128 v[186:189], v199 offset:17408
	ds_read_b128 v[212:215], v199 offset:18432
	s_mov_b32 m0, s52
	v_lshl_add_u64 v[172:173], s[30:31], 0, v[0:1]
	global_load_lds_dwordx4 v[172:173], off
	ds_read_b128 v[216:219], v199 offset:19456
	ds_read_b128 v[220:223], v199 offset:20480
	s_add_i32 m0, s52, 0x2000
	s_add_u32 s52, s30, 0x20000
	v_lshl_add_u64 v[174:175], s[30:31], 0, v[166:167]
	s_addc_u32 s53, s31, 0
	s_add_i32 s54, s54, s36
	global_load_lds_dwordx4 v[174:175], off
	ds_read_b128 v[224:227], v199 offset:21504
	ds_read_b128 v[228:231], v199 offset:22528
	s_mov_b32 m0, s54
	v_lshl_add_u64 v[244:245], s[52:53], 0, v[0:1]
	global_load_lds_dwordx4 v[244:245], off
	ds_read_b128 v[232:235], v199 offset:23552
	s_add_i32 m0, s54, 0x2000
	v_lshl_add_u64 v[244:245], s[52:53], 0, v[166:167]
	global_load_lds_dwordx4 v[244:245], off
	s_waitcnt vmcnt(8)
	s_waitcnt lgkmcnt(0)
	s_barrier
; #define PG8_STAGE(bufoff, gbase, voff) do { _Pragma("unroll") for (int _i = 0; _i < 2; ++_i) \
;         __builtin_amdgcn_global_load_lds((const unsigned*)((const char*)(gbase) + (voff)[_i]), (LAS unsigned*)(lds + (bufoff) + ldsw + _i * 8192), 16, 0, 0); } while (0)
; #define PG8_LDA(dst, b, h) do { _Pragma("unroll") for (int m = 0; m < 4; ++m) _Pragma("unroll") for (int k = 0; k < 2; ++k) dst[m][k] = *(const LAS bf16x8*)(lds + PG8_SA(b, h) + aoff + m * 2048 + k * 1024); } while (0)
; #define PG8_LDB(dst, b, h) do { _Pragma("unroll") for (int n = 0; n < 2; ++n) _Pragma("unroll") for (int k = 0; k < 2; ++k) dst[n][k] = *(const LAS bf16x8*)(lds + PG8_SB(b, h) + boff + n * 2048 + k * 1024); } while (0)
; #define PG8_MMA(ai, bj, At, Bt) do { __builtin_amdgcn_s_setprio(1); _Pragma("unroll") for (int m = 0; m < 4; ++m) _Pragma("unroll") for (int n = 0; n < 2; ++n) _Pragma("unroll") for (int k = 0; k < 2; ++k) \
;         acc[ai][bj][m][n] = __builtin_amdgcn_mfma_f32_16x16x32_bf16(Bt[n][k], At[m][k], acc[ai][bj][m][n], 0, 0, 0); __builtin_amdgcn_s_setprio(0); } while (0)
; #define PG8_WAIT_V(n) asm volatile("s_waitcnt vmcnt(" #n ")" ::: "memory")
; #define PG8_WAIT_L(n) asm volatile("s_waitcnt lgkmcnt(" #n ")" ::: "memory")
; #define PG8_BAR __builtin_amdgcn_s_barrier()
; #define PG8_SCHED __builtin_amdgcn_sched_barrier(0)
; template <class Epi>
; __device__ __forceinline__ void gemm_phase(LAS unsigned char* lds, const Gemm g, const StaticOrder& S, const Epi& E, const int tid) {
;     ...
;             PG8_WAIT_V(8); PG8_WAIT_L(0); PG8_BAR; PG8_MMA(1, 0, At, B0); PG8_MMA(1, 1, At, B1); PG8_BAR; PG8_SCHED;
;             PG8_LDB(B0, 1, 0); PG8_LDB(B1, 1, 1); PG8_SCHED; PG8_LDA(At, 1, 0); PG8_STAGE(PG8_SA(0, 1), a2 + hstep, voffA);
;             PG8_WAIT_V(8); PG8_WAIT_L(0); PG8_BAR; PG8_MMA(0, 0, At, B0); PG8_MMA(0, 1, At, B1); PG8_BAR; PG8_SCHED;
	s_setprio 1
	v_mfma_f32_16x16x32_bf16 v[94:97], v[18:21], v[182:185], v[94:97]
	v_mfma_f32_16x16x32_bf16 v[90:93], v[26:29], v[182:185], v[90:93]
	v_mfma_f32_16x16x32_bf16 v[78:81], v[18:21], v[212:215], v[78:81]
	v_mfma_f32_16x16x32_bf16 v[74:77], v[26:29], v[212:215], v[74:77]
	v_mfma_f32_16x16x32_bf16 v[62:65], v[18:21], v[220:223], v[62:65]
	v_mfma_f32_16x16x32_bf16 v[58:61], v[26:29], v[220:223], v[58:61]
	v_mfma_f32_16x16x32_bf16 v[14:17], v[18:21], v[228:231], v[14:17]
	v_mfma_f32_16x16x32_bf16 v[10:13], v[26:29], v[228:231], v[10:13]
	v_mfma_f32_16x16x32_bf16 v[94:97], v[22:25], v[186:189], v[94:97]
	v_mfma_f32_16x16x32_bf16 v[90:93], v[30:33], v[186:189], v[90:93]
	v_mfma_f32_16x16x32_bf16 v[78:81], v[22:25], v[216:219], v[78:81]
	v_mfma_f32_16x16x32_bf16 v[74:77], v[30:33], v[216:219], v[74:77]
	v_mfma_f32_16x16x32_bf16 v[62:65], v[22:25], v[224:227], v[62:65]
	v_mfma_f32_16x16x32_bf16 v[58:61], v[30:33], v[224:227], v[58:61]
	v_mfma_f32_16x16x32_bf16 v[14:17], v[22:25], v[232:235], v[14:17]
	v_mfma_f32_16x16x32_bf16 v[10:13], v[30:33], v[232:235], v[10:13]
	v_mfma_f32_16x16x32_bf16 v[38:41], v[42:45], v[220:223], v[38:41]
	v_mfma_f32_16x16x32_bf16 v[34:37], v[50:53], v[220:223], v[34:37]
	v_mfma_f32_16x16x32_bf16 v[6:9], v[42:45], v[228:231], v[6:9]
	v_mfma_f32_16x16x32_bf16 v[2:5], v[50:53], v[228:231], v[2:5]
	v_mfma_f32_16x16x32_bf16 v[18:21], v[42:45], v[182:185], v[86:89]
	v_mfma_f32_16x16x32_bf16 v[22:25], v[50:53], v[182:185], v[82:85]
	v_mfma_f32_16x16x32_bf16 v[26:29], v[42:45], v[212:215], v[70:73]
	v_mfma_f32_16x16x32_bf16 v[30:33], v[50:53], v[212:215], v[66:69]
	v_mfma_f32_16x16x32_bf16 v[38:41], v[46:49], v[224:227], v[38:41]
	v_mfma_f32_16x16x32_bf16 v[34:37], v[54:57], v[224:227], v[34:37]
	v_mfma_f32_16x16x32_bf16 v[6:9], v[46:49], v[232:235], v[6:9]
	v_mfma_f32_16x16x32_bf16 v[2:5], v[54:57], v[232:235], v[2:5]
	v_mfma_f32_16x16x32_bf16 v[18:21], v[46:49], v[186:189], v[18:21]
	v_mfma_f32_16x16x32_bf16 v[22:25], v[54:57], v[186:189], v[22:25]
	v_mfma_f32_16x16x32_bf16 v[26:29], v[46:49], v[216:219], v[26:29]
	v_mfma_f32_16x16x32_bf16 v[30:33], v[54:57], v[216:219], v[30:33]
	s_setprio 0
	s_barrier
	s_add_i32 s52, 0, 0x18000
	s_add_i32 s53, 0, 0x1c000
	v_add_u32_e32 v54, s52, v193
	v_add_u32_e32 v66, s53, v193
	ds_read_b128 v[42:45], v54
	ds_read_b128 v[46:49], v54 offset:1024
	ds_read_b128 v[50:53], v54 offset:2048
	ds_read_b128 v[54:57], v54 offset:3072
	ds_read_b128 v[182:185], v66
	ds_read_b128 v[186:189], v66 offset:1024
	ds_read_b128 v[212:215], v66 offset:2048
	ds_read_b128 v[216:219], v66 offset:3072
	s_add_u32 s34, s34, 0x200000
	s_addc_u32 s35, s35, 0
	s_mov_b32 m0, s39
	v_lshl_add_u64 v[236:237], s[34:35], 0, v[162:163]
	ds_read_b128 v[66:69], v199 offset:32768
	global_load_lds_dwordx4 v[236:237], off
	ds_read_b128 v[70:73], v199 offset:33792
	ds_read_b128 v[82:85], v199 offset:34816
	s_mov_b32 m0, s44
	v_lshl_add_u64 v[236:237], s[34:35], 0, v[164:165]
	global_load_lds_dwordx4 v[236:237], off
	ds_read_b128 v[86:89], v199 offset:35840
	ds_read_b128 v[220:223], v199 offset:36864
	ds_read_b128 v[224:227], v199 offset:37888
	ds_read_b128 v[228:231], v199 offset:38912
	ds_read_b128 v[232:235], v199 offset:39936
	s_waitcnt vmcnt(8)
	s_waitcnt lgkmcnt(0)
	s_barrier
	s_setprio 1
	v_mfma_f32_16x16x32_bf16 v[158:161], v[42:45], v[66:69], v[158:161]
	v_mfma_f32_16x16x32_bf16 v[154:157], v[50:53], v[66:69], v[154:157]
	v_mfma_f32_16x16x32_bf16 v[142:145], v[42:45], v[82:85], v[142:145]
	v_mfma_f32_16x16x32_bf16 v[138:141], v[50:53], v[82:85], v[138:141]
	v_mfma_f32_16x16x32_bf16 v[126:129], v[42:45], v[220:223], v[126:129]
	v_mfma_f32_16x16x32_bf16 v[122:125], v[50:53], v[220:223], v[122:125]
	v_mfma_f32_16x16x32_bf16 v[110:113], v[42:45], v[228:231], v[110:113]
	v_mfma_f32_16x16x32_bf16 v[106:109], v[50:53], v[228:231], v[106:109]
	v_mfma_f32_16x16x32_bf16 v[158:161], v[46:49], v[70:73], v[158:161]
	v_mfma_f32_16x16x32_bf16 v[154:157], v[54:57], v[70:73], v[154:157]
	v_mfma_f32_16x16x32_bf16 v[142:145], v[46:49], v[86:89], v[142:145]
	v_mfma_f32_16x16x32_bf16 v[138:141], v[54:57], v[86:89], v[138:141]
	v_mfma_f32_16x16x32_bf16 v[126:129], v[46:49], v[224:227], v[126:129]
	v_mfma_f32_16x16x32_bf16 v[122:125], v[54:57], v[224:227], v[122:125]
	v_mfma_f32_16x16x32_bf16 v[110:113], v[46:49], v[232:235], v[110:113]
	v_mfma_f32_16x16x32_bf16 v[106:109], v[54:57], v[232:235], v[106:109]
	v_mfma_f32_16x16x32_bf16 v[150:153], v[182:185], v[66:69], v[150:153]
	v_mfma_f32_16x16x32_bf16 v[66:69], v[212:215], v[66:69], v[146:149]
	v_mfma_f32_16x16x32_bf16 v[146:149], v[216:219], v[70:73], v[66:69]
	v_mfma_f32_16x16x32_bf16 v[66:69], v[182:185], v[82:85], v[134:137]
	v_mfma_f32_16x16x32_bf16 v[134:137], v[186:189], v[86:89], v[66:69]
	v_mfma_f32_16x16x32_bf16 v[66:69], v[212:215], v[82:85], v[130:133]
	v_mfma_f32_16x16x32_bf16 v[130:133], v[216:219], v[86:89], v[66:69]
	v_mfma_f32_16x16x32_bf16 v[66:69], v[182:185], v[220:223], v[118:121]
	v_mfma_f32_16x16x32_bf16 v[118:121], v[186:189], v[224:227], v[66:69]
	v_mfma_f32_16x16x32_bf16 v[66:69], v[212:215], v[220:223], v[114:117]
	v_mfma_f32_16x16x32_bf16 v[114:117], v[216:219], v[224:227], v[66:69]
	v_mfma_f32_16x16x32_bf16 v[66:69], v[182:185], v[228:231], v[102:105]
	v_mfma_f32_16x16x32_bf16 v[102:105], v[186:189], v[232:235], v[66:69]
	v_mfma_f32_16x16x32_bf16 v[66:69], v[212:215], v[228:231], v[98:101]
	v_mfma_f32_16x16x32_bf16 v[150:153], v[186:189], v[70:73], v[150:153]
	v_mfma_f32_16x16x32_bf16 v[98:101], v[216:219], v[232:235], v[66:69]
	s_setprio 0
	s_barrier
; #define PG8_STAGE(bufoff, gbase, voff) do { _Pragma("unroll") for (int _i = 0; _i < 2; ++_i) \
;         __builtin_amdgcn_global_load_lds((const unsigned*)((const char*)(gbase) + (voff)[_i]), (LAS unsigned*)(lds + (bufoff) + ldsw + _i * 8192), 16, 0, 0); } while (0)
; #define PG8_LDA(dst, b, h) do { _Pragma("unroll") for (int m = 0; m < 4; ++m) _Pragma("unroll") for (int k = 0; k < 2; ++k) dst[m][k] = *(const LAS bf16x8*)(lds + PG8_SA(b, h) + aoff + m * 2048 + k * 1024); } while (0)
; #define PG8_MMA(ai, bj, At, Bt) do { __builtin_amdgcn_s_setprio(1); _Pragma("unroll") for (int m = 0; m < 4; ++m) _Pragma("unroll") for (int n = 0; n < 2; ++n) _Pragma("unroll") for (int k = 0; k < 2; ++k) \
;         acc[ai][bj][m][n] = __builtin_amdgcn_mfma_f32_16x16x32_bf16(Bt[n][k], At[m][k], acc[ai][bj][m][n], 0, 0, 0); __builtin_amdgcn_s_setprio(0); } while (0)
; #define PG8_WAIT_V(n) asm volatile("s_waitcnt vmcnt(" #n ")" ::: "memory")
; #define PG8_WAIT_L(n) asm volatile("s_waitcnt lgkmcnt(" #n ")" ::: "memory")
; #define PG8_BAR __builtin_amdgcn_s_barrier()
; #define PG8_SCHED __builtin_amdgcn_sched_barrier(0)
; template <class Epi>
; __device__ __forceinline__ void gemm_phase(LAS unsigned char* lds, const Gemm g, const StaticOrder& S, const Epi& E, const int tid) {
;     ...
;             PG8_LDA(At, 1, 1); PG8_STAGE(PG8_SB(1, 0), b3, voffB); PG8_STAGE(PG8_SB(1, 1), b3 + bhs, voffB); PG8_STAGE(PG8_SA(1, 0), a3, voffA);
;             PG8_WAIT_V(8); PG8_WAIT_L(0); PG8_BAR; PG8_MMA(1, 0, At, B0); PG8_MMA(1, 1, At, B1); PG8_BAR; PG8_SCHED;
;     ...
;         if (ALIGN_EPI) { if (wr == 0) PG8_BAR; }
	s_add_i32 s34, s52, s36
	s_mov_b32 m0, s45
	v_lshl_add_u64 v[82:83], v[176:177], 0, s[70:71]
	ds_read_b128 v[66:69], v199 offset:49152
	global_load_lds_dwordx4 v[82:83], off
	s_mov_b32 m0, s46
	v_lshl_add_u64 v[82:83], v[200:201], 0, s[70:71]
	global_load_lds_dwordx4 v[82:83], off
	ds_read_b128 v[70:73], v199 offset:50176
	ds_read_b128 v[220:223], v199 offset:51200
	s_mov_b32 m0, s34
	v_lshl_add_u64 v[82:83], v[172:173], 0, s[70:71]
	global_load_lds_dwordx4 v[82:83], off
	ds_read_b128 v[224:227], v199 offset:52224
	ds_read_b128 v[228:231], v199 offset:53248
	s_add_i32 m0, s34, 0x2000
	s_add_u32 s30, s30, 0x20080
	v_lshl_add_u64 v[82:83], v[174:175], 0, s[70:71]
	s_addc_u32 s31, s31, 0
	s_add_i32 s34, s53, s36
	global_load_lds_dwordx4 v[82:83], off
	ds_read_b128 v[232:235], v199 offset:54272
	ds_read_b128 v[236:239], v199 offset:55296
	s_mov_b32 m0, s34
	v_lshl_add_u64 v[82:83], s[30:31], 0, v[0:1]
	global_load_lds_dwordx4 v[82:83], off
	ds_read_b128 v[240:243], v199 offset:56320
	s_add_i32 m0, s34, 0x2000
	v_lshl_add_u64 v[82:83], s[30:31], 0, v[166:167]
	global_load_lds_dwordx4 v[82:83], off
	s_waitcnt vmcnt(8)
	s_waitcnt lgkmcnt(0)
	s_barrier
	s_setprio 1
	v_mfma_f32_16x16x32_bf16 v[82:85], v[42:45], v[66:69], v[94:97]
	v_mfma_f32_16x16x32_bf16 v[94:97], v[46:49], v[70:73], v[82:85]
	v_mfma_f32_16x16x32_bf16 v[82:85], v[50:53], v[66:69], v[90:93]
	v_mfma_f32_16x16x32_bf16 v[78:81], v[42:45], v[220:223], v[78:81]
	v_mfma_f32_16x16x32_bf16 v[74:77], v[50:53], v[220:223], v[74:77]
	v_mfma_f32_16x16x32_bf16 v[62:65], v[42:45], v[228:231], v[62:65]
	v_mfma_f32_16x16x32_bf16 v[58:61], v[50:53], v[228:231], v[58:61]
	v_mfma_f32_16x16x32_bf16 v[14:17], v[42:45], v[236:239], v[14:17]
	v_mfma_f32_16x16x32_bf16 v[10:13], v[50:53], v[236:239], v[10:13]
	v_mfma_f32_16x16x32_bf16 v[90:93], v[54:57], v[70:73], v[82:85]
	v_mfma_f32_16x16x32_bf16 v[78:81], v[46:49], v[224:227], v[78:81]
	v_mfma_f32_16x16x32_bf16 v[74:77], v[54:57], v[224:227], v[74:77]
	v_mfma_f32_16x16x32_bf16 v[62:65], v[46:49], v[232:235], v[62:65]
	v_mfma_f32_16x16x32_bf16 v[58:61], v[54:57], v[232:235], v[58:61]
	v_mfma_f32_16x16x32_bf16 v[14:17], v[46:49], v[240:243], v[14:17]
	v_mfma_f32_16x16x32_bf16 v[10:13], v[54:57], v[240:243], v[10:13]
	v_mfma_f32_16x16x32_bf16 v[18:21], v[182:185], v[66:69], v[18:21]
	v_mfma_f32_16x16x32_bf16 v[86:89], v[186:189], v[70:73], v[18:21]
	v_mfma_f32_16x16x32_bf16 v[18:21], v[212:215], v[66:69], v[22:25]
	v_mfma_f32_16x16x32_bf16 v[82:85], v[216:219], v[70:73], v[18:21]
	v_mfma_f32_16x16x32_bf16 v[18:21], v[182:185], v[220:223], v[26:29]
	v_mfma_f32_16x16x32_bf16 v[70:73], v[186:189], v[224:227], v[18:21]
	v_mfma_f32_16x16x32_bf16 v[18:21], v[212:215], v[220:223], v[30:33]
	v_mfma_f32_16x16x32_bf16 v[66:69], v[216:219], v[224:227], v[18:21]
	v_mfma_f32_16x16x32_bf16 v[18:21], v[182:185], v[228:231], v[38:41]
	v_mfma_f32_16x16x32_bf16 v[38:41], v[186:189], v[232:235], v[18:21]
	v_mfma_f32_16x16x32_bf16 v[18:21], v[212:215], v[228:231], v[34:37]
	v_mfma_f32_16x16x32_bf16 v[6:9], v[182:185], v[236:239], v[6:9]
	v_mfma_f32_16x16x32_bf16 v[2:5], v[212:215], v[236:239], v[2:5]
	v_mfma_f32_16x16x32_bf16 v[34:37], v[216:219], v[232:235], v[18:21]
	v_mfma_f32_16x16x32_bf16 v[6:9], v[186:189], v[240:243], v[6:9]
	v_mfma_f32_16x16x32_bf16 v[2:5], v[216:219], v[240:243], v[2:5]
	s_setprio 0
	s_barrier
	s_add_i32 s51, s51, 2
	s_add_u32 s49, s49, 0x100
	s_addc_u32 s50, s50, 0
	s_add_u32 s28, s28, 0x100
	s_addc_u32 s29, s29, 0
	s_cmpk_gt_u32 s51, 0x7d
	s_cbranch_scc0 .LBB0_126
	s_and_b64 vcc, exec, s[12:13]
	s_cbranch_vccz .LBB0_129
	s_barrier
